# per-item softmax sum / last-tile max shuffles in the MLA and NA item epilogues also via permlane swaps (on top of the DPP norm reductions)
# baseline (speedup 1.0000x reference)
.LBB0_332:
	v_fma_f32 v0, v70, s17, -v144
	v_exp_f32_e32 v0, v0
	v_fma_f32 v44, v71, s17, -v144
	v_exp_f32_e32 v44, v44
	v_fma_f32 v45, v72, s17, -v144
	v_exp_f32_e32 v45, v45
	v_fma_f32 v46, v73, s17, -v144
	v_exp_f32_e32 v46, v46
	v_add_f32_e32 v47, 0, v0
	v_add_f32_e32 v47, v44, v47
	v_add_f32_e32 v47, v45, v47
	v_cvt_pk_bf16_f32 v44, v0, v44
	v_fma_f32 v0, v66, s17, -v144
	v_add_f32_e32 v47, v46, v47
	v_cvt_pk_bf16_f32 v45, v45, v46
	v_exp_f32_e32 v0, v0
	v_fma_f32 v46, v67, s17, -v144
	v_exp_f32_e32 v46, v46
	v_fma_f32 v48, v68, s17, -v144
	v_exp_f32_e32 v48, v48
	v_fma_f32 v49, v69, s17, -v144
	v_exp_f32_e32 v49, v49
	v_add_f32_e32 v47, v0, v47
	v_add_f32_e32 v47, v46, v47
	v_add_f32_e32 v47, v48, v47
	v_cvt_pk_bf16_f32 v46, v0, v46
	v_fma_f32 v0, v62, s17, -v144
	v_add_f32_e32 v66, v49, v47
	v_cvt_pk_bf16_f32 v47, v48, v49
	v_exp_f32_e32 v0, v0
	v_fma_f32 v48, v63, s17, -v144
	v_exp_f32_e32 v48, v48
	v_fma_f32 v49, v64, s17, -v144
	v_exp_f32_e32 v49, v49
	v_fma_f32 v62, v65, s17, -v144
	v_exp_f32_e32 v63, v62
	v_add_f32_e32 v62, v0, v66
	v_add_f32_e32 v62, v48, v62
	v_add_f32_e32 v62, v49, v62
	v_add_f32_e32 v64, v63, v62
	v_cvt_pk_bf16_f32 v62, v0, v48
	v_fma_f32 v0, v38, s17, -v144
	v_exp_f32_e32 v0, v0
	v_fma_f32 v38, v39, s17, -v144
	v_exp_f32_e32 v38, v38
	v_fma_f32 v39, v40, s17, -v144
	v_exp_f32_e32 v39, v39
	v_fma_f32 v40, v41, s17, -v144
	v_exp_f32_e32 v40, v40
	v_add_f32_e32 v41, v0, v64
	v_add_f32_e32 v41, v38, v41
	v_add_f32_e32 v41, v39, v41
	v_cvt_pk_bf16_f32 v64, v0, v38
	v_fma_f32 v38, v58, s17, -v142
	v_add_f32_e32 v41, v40, v41
	v_cvt_pk_bf16_f32 v65, v39, v40
	v_exp_f32_e32 v38, v38
	v_fma_f32 v39, v59, s17, -v142
	v_add_f32_e32 v0, v140, v41
	v_exp_f32_e32 v39, v39
	v_fma_f32 v40, v60, s17, -v142
	v_fma_f32 v41, v61, s17, -v142
	v_exp_f32_e32 v40, v40
	v_exp_f32_e32 v41, v41
	v_add_f32_e32 v48, 0, v38
	v_add_f32_e32 v48, v39, v48
	v_add_f32_e32 v48, v40, v48
	v_cvt_pk_bf16_f32 v38, v38, v39
	v_cvt_pk_bf16_f32 v39, v40, v41
	v_fma_f32 v40, v54, s17, -v142
	v_add_f32_e32 v48, v41, v48
	v_exp_f32_e32 v40, v40
	v_fma_f32 v41, v55, s17, -v142
	v_cvt_pk_bf16_f32 v63, v49, v63
	v_exp_f32_e32 v41, v41
	v_fma_f32 v49, v56, s17, -v142
	v_fma_f32 v54, v57, s17, -v142
	v_exp_f32_e32 v49, v49
	v_exp_f32_e32 v54, v54
	v_add_f32_e32 v48, v40, v48
	v_add_f32_e32 v48, v41, v48
	v_add_f32_e32 v48, v49, v48
	v_cvt_pk_bf16_f32 v40, v40, v41
	v_cvt_pk_bf16_f32 v41, v49, v54
	v_fma_f32 v49, v50, s17, -v142
	v_exp_f32_e32 v49, v49
	v_fma_f32 v50, v51, s17, -v142
	v_exp_f32_e32 v50, v50
	v_fma_f32 v51, v52, s17, -v142
	v_exp_f32_e32 v51, v51
	v_fma_f32 v52, v53, s17, -v142
	v_add_f32_e32 v48, v54, v48
	v_exp_f32_e32 v52, v52
	v_add_f32_e32 v48, v49, v48
	v_add_f32_e32 v48, v50, v48
	v_add_f32_e32 v48, v51, v48
	v_fma_f32 v34, v34, s17, -v142
	v_add_f32_e32 v53, v52, v48
	v_cvt_pk_bf16_f32 v48, v49, v50
	v_exp_f32_e32 v50, v34
	v_fma_f32 v34, v35, s17, -v142
	v_exp_f32_e32 v60, v34
	v_fma_f32 v34, v36, s17, -v142
	v_exp_f32_e32 v61, v34
	v_add_f32_e32 v34, v50, v53
	v_add_f32_e32 v34, v60, v34
	v_cvt_pk_bf16_f32 v49, v51, v52
	v_add_f32_e32 v51, v61, v34
	v_fma_f32 v34, v37, s17, -v142
	v_exp_f32_e32 v70, v34
	v_mul_u32_u24_e32 v34, 0x48, v135
	v_lshl_add_u32 v71, v34, 1, v136
	ds_read_b64_tr_b16 v[36:37], v71 offset:20736
	ds_read_b64_tr_b16 v[34:35], v71 offset:18432
	ds_read_b64_tr_b16 v[54:55], v71 offset:20768
	ds_read_b64_tr_b16 v[52:53], v71 offset:18464
	ds_read_b64_tr_b16 v[56:57], v71 offset:23040
	ds_read_b64_tr_b16 v[58:59], v71 offset:25344
	ds_read_b64_tr_b16 v[68:69], v71 offset:25376
	ds_read_b64_tr_b16 v[66:67], v71 offset:23072
	v_add_f32_e32 v72, v70, v51
	v_cvt_pk_bf16_f32 v50, v50, v60
	v_cvt_pk_bf16_f32 v51, v61, v70
	v_add_f32_e32 v60, v137, v72
	s_waitcnt lgkmcnt(6)
	v_mfma_f32_16x16x32_bf16 v[18:21], v[34:37], v[44:47], v[18:21]
	v_mfma_f32_16x16x32_bf16 v[30:33], v[34:37], v[38:41], v[30:33]
	s_waitcnt lgkmcnt(4)
	v_mfma_f32_16x16x32_bf16 v[22:25], v[52:55], v[44:47], v[22:25]
	v_mfma_f32_16x16x32_bf16 v[26:29], v[52:55], v[38:41], v[26:29]
	s_waitcnt lgkmcnt(2)
	v_mfma_f32_16x16x32_bf16 v[18:21], v[56:59], v[62:65], v[18:21]
	v_mfma_f32_16x16x32_bf16 v[30:33], v[56:59], v[48:51], v[30:33]
	s_waitcnt lgkmcnt(0)
	v_mfma_f32_16x16x32_bf16 v[22:25], v[66:69], v[62:65], v[22:25]
	v_mfma_f32_16x16x32_bf16 v[26:29], v[66:69], v[48:51], v[26:29]
	ds_read_b64_tr_b16 v[36:37], v71 offset:20800
	ds_read_b64_tr_b16 v[34:35], v71 offset:18496
	ds_read_b64_tr_b16 v[54:55], v71 offset:20832
	ds_read_b64_tr_b16 v[52:53], v71 offset:18528
	ds_read_b64_tr_b16 v[56:57], v71 offset:23104
	ds_read_b64_tr_b16 v[58:59], v71 offset:25408
	ds_read_b64_tr_b16 v[68:69], v71 offset:25440
	ds_read_b64_tr_b16 v[66:67], v71 offset:23136
	s_waitcnt lgkmcnt(6)
	v_mfma_f32_16x16x32_bf16 v[10:13], v[34:37], v[44:47], v[10:13]
	v_mfma_f32_16x16x32_bf16 v[14:17], v[34:37], v[38:41], v[14:17]
	s_waitcnt lgkmcnt(4)
	v_mfma_f32_16x16x32_bf16 v[2:5], v[52:55], v[44:47], v[2:5]
	v_mfma_f32_16x16x32_bf16 v[6:9], v[52:55], v[38:41], v[6:9]
	s_waitcnt lgkmcnt(2)
	v_mfma_f32_16x16x32_bf16 v[10:13], v[56:59], v[62:65], v[10:13]
	v_mfma_f32_16x16x32_bf16 v[14:17], v[56:59], v[48:51], v[14:17]
	s_waitcnt lgkmcnt(0)
	v_mfma_f32_16x16x32_bf16 v[2:5], v[66:69], v[62:65], v[2:5]
	v_mfma_f32_16x16x32_bf16 v[6:9], v[66:69], v[48:51], v[6:9]
	v_mov_b32_e32 v34, v0
	s_nop 1
	v_permlane16_swap_b32_e32 v34, v0
	s_barrier
	s_add_i32 s34, s34, 1
	v_add_f32_e32 v0, v0, v34
	v_mov_b32_e32 v34, v0
	s_nop 1
	v_permlane32_swap_b32_e32 v34, v0
	s_cmp_eq_u32 s34, 8
	v_add_f32_e32 v0, v0, v34
	v_div_scale_f32 v36, s[2:3], v0, v0, 1.0
	v_rcp_f32_e32 v37, v36
	v_div_scale_f32 v38, vcc, 1.0, v0, 1.0
	v_lshlrev_b64 v[34:35], 11, v[122:123]
	v_fma_f32 v39, -v36, v37, 1.0
	v_fmac_f32_e32 v37, v39, v37
	v_mul_f32_e32 v39, v38, v37
	v_fma_f32 v40, -v36, v39, v38
	v_fmac_f32_e32 v39, v40, v37
	v_fma_f32 v36, -v36, v39, v38
	v_div_fmas_f32 v36, v36, v37, v39
	v_div_fixup_f32 v36, v36, v0, 1.0
	v_pk_mul_f32 v[18:19], v[18:19], v[36:37] op_sel_hi:[1,0]
	v_pk_mul_f32 v[20:21], v[20:21], v[36:37] op_sel_hi:[1,0]
	v_mov_b32_e32 v0, v21
	v_mov_b32_e32 v21, v19
	v_cvt_pk_bf16_f32 v19, v20, v0
	v_cvt_pk_bf16_f32 v18, v18, v21
	v_lshl_add_u64 v[20:21], v[118:119], 0, v[34:35]
	v_lshlrev_b32_e32 v0, 1, v134
	v_lshl_add_u64 v[20:21], v[20:21], 0, v[0:1]
	global_store_dwordx2 v[20:21], v[18:19], off
	v_pk_mul_f32 v[18:19], v[22:23], v[36:37] op_sel_hi:[1,0]
	v_pk_mul_f32 v[22:23], v[24:25], v[36:37] op_sel_hi:[1,0]
	v_mov_b32_e32 v24, v19
	v_cvt_pk_bf16_f32 v19, v22, v23
	v_cvt_pk_bf16_f32 v18, v18, v24
	v_pk_mul_f32 v[10:11], v[10:11], v[36:37] op_sel_hi:[1,0]
	v_pk_mul_f32 v[12:13], v[12:13], v[36:37] op_sel_hi:[1,0]
	global_store_dwordx2 v[20:21], v[18:19], off offset:32
	v_mov_b32_e32 v18, v11
	v_cvt_pk_bf16_f32 v11, v12, v13
	v_cvt_pk_bf16_f32 v10, v10, v18
	global_store_dwordx2 v[20:21], v[10:11], off offset:64
	v_mov_b32_e32 v10, v60
	s_nop 1
	v_permlane16_swap_b32_e32 v10, v60
	v_pk_mul_f32 v[4:5], v[4:5], v[36:37] op_sel_hi:[1,0]
	v_pk_mul_f32 v[2:3], v[2:3], v[36:37] op_sel_hi:[1,0]
	v_add_f32_e32 v10, v60, v10
	v_mov_b32_e32 v19, v10
	s_nop 1
	v_permlane32_swap_b32_e32 v19, v10
	v_mov_b32_e32 v11, v3
	v_add_f32_e32 v10, v10, v19
	v_div_scale_f32 v12, s[2:3], v10, v10, 1.0
	v_rcp_f32_e32 v13, v12
	v_cvt_pk_bf16_f32 v3, v4, v5
	v_cvt_pk_bf16_f32 v2, v2, v11
	global_store_dwordx2 v[20:21], v[2:3], off offset:96
	v_fma_f32 v2, -v12, v13, 1.0
	v_fmac_f32_e32 v13, v2, v13
	v_div_scale_f32 v2, vcc, 1.0, v10, 1.0
	v_mul_f32_e32 v3, v2, v13
	v_fma_f32 v4, -v12, v3, v2
	v_fmac_f32_e32 v3, v4, v13
	v_fma_f32 v2, -v12, v3, v2
	v_div_fmas_f32 v2, v2, v13, v3
	v_div_fixup_f32 v2, v2, v10, 1.0
	v_pk_mul_f32 v[10:11], v[30:31], v[2:3] op_sel_hi:[1,0]
	v_pk_mul_f32 v[12:13], v[32:33], v[2:3] op_sel_hi:[1,0]
	v_lshlrev_b64 v[4:5], 11, v[120:121]
	v_bfe_u32 v3, v13, 16, 1
	v_bfe_u32 v18, v12, 16, 1
	v_add3_u32 v12, v12, v18, s0
	v_add3_u32 v3, v13, v3, s0
	v_mov_b32_e32 v13, v11
	v_lshl_add_u64 v[4:5], v[118:119], 0, v[4:5]
	v_perm_b32 v11, v3, v12, s19
	v_cvt_pk_bf16_f32 v10, v10, v13
	v_lshl_add_u64 v[4:5], v[4:5], 0, v[0:1]
	global_store_dwordx2 v[4:5], v[10:11], off
	v_pk_mul_f32 v[10:11], v[26:27], v[2:3] op_sel_hi:[1,0]
	v_pk_mul_f32 v[12:13], v[28:29], v[2:3] op_sel_hi:[1,0]
	v_bfe_u32 v0, v13, 16, 1
	v_bfe_u32 v3, v12, 16, 1
	v_add3_u32 v3, v12, v3, s0
	v_add3_u32 v0, v13, v0, s0
	v_mov_b32_e32 v12, v11
	v_perm_b32 v11, v0, v3, s19
	v_cvt_pk_bf16_f32 v10, v10, v12
	global_store_dwordx2 v[4:5], v[10:11], off offset:32
	v_pk_mul_f32 v[10:11], v[14:15], v[2:3] op_sel_hi:[1,0]
	v_pk_mul_f32 v[12:13], v[16:17], v[2:3] op_sel_hi:[1,0]
	v_bfe_u32 v0, v13, 16, 1
	v_bfe_u32 v3, v12, 16, 1
	v_add3_u32 v3, v12, v3, s0
	v_add3_u32 v0, v13, v0, s0
	v_mov_b32_e32 v12, v11
	v_perm_b32 v11, v0, v3, s19
	v_cvt_pk_bf16_f32 v10, v10, v12
	v_pk_mul_f32 v[6:7], v[6:7], v[2:3] op_sel_hi:[1,0]
	v_pk_mul_f32 v[2:3], v[8:9], v[2:3] op_sel_hi:[1,0]
	global_store_dwordx2 v[4:5], v[10:11], off offset:64
	v_cvt_pk_bf16_f32 v3, v2, v3
	v_cvt_pk_bf16_f32 v2, v6, v7
	global_store_dwordx2 v[4:5], v[2:3], off offset:96
	s_cbranch_scc1 .LBB0_423

.LBB0_419:
	v_mad_u32_u24 v0, v138, s16, v145
	ds_read_b128 v[50:53], v0
	ds_read_b128 v[54:57], v0 offset:64
	ds_read_b128 v[62:65], v0 offset:2304
	ds_read_b128 v[74:77], v0 offset:2368
	ds_read_b128 v[78:81], v0 offset:4608
	ds_read_b128 v[82:85], v0 offset:4672
	ds_read_b128 v[86:89], v0 offset:6912
	ds_read_b128 v[90:93], v0 offset:6976
	s_waitcnt lgkmcnt(7)
	v_mfma_f32_16x16x32_bf16 v[58:61], v[50:53], v[38:41], 0
	v_mfma_f32_16x16x32_bf16 v[50:53], v[50:53], v[46:49], 0
	s_waitcnt lgkmcnt(6)
	v_mfma_f32_16x16x32_bf16 v[70:73], v[54:57], v[34:37], v[58:61]
	v_mfma_f32_16x16x32_bf16 v[58:61], v[54:57], v[42:45], v[50:53]
	s_waitcnt lgkmcnt(5)
	v_mfma_f32_16x16x32_bf16 v[50:53], v[62:65], v[38:41], 0
	v_mfma_f32_16x16x32_bf16 v[54:57], v[62:65], v[46:49], 0
	s_waitcnt lgkmcnt(4)
	v_mfma_f32_16x16x32_bf16 v[66:69], v[74:77], v[34:37], v[50:53]
	v_mfma_f32_16x16x32_bf16 v[54:57], v[74:77], v[42:45], v[54:57]
	s_waitcnt lgkmcnt(3)
	v_mfma_f32_16x16x32_bf16 v[50:53], v[78:81], v[38:41], 0
	v_mfma_f32_16x16x32_bf16 v[74:77], v[78:81], v[46:49], 0
	s_waitcnt lgkmcnt(1)
	v_mfma_f32_16x16x32_bf16 v[38:41], v[86:89], v[38:41], 0
	v_mfma_f32_16x16x32_bf16 v[46:49], v[86:89], v[46:49], 0
	v_mfma_f32_16x16x32_bf16 v[62:65], v[82:85], v[34:37], v[50:53]
	v_mfma_f32_16x16x32_bf16 v[50:53], v[82:85], v[42:45], v[74:77]
	s_waitcnt lgkmcnt(0)
	v_mfma_f32_16x16x32_bf16 v[38:41], v[90:93], v[34:37], v[38:41]
	v_mfma_f32_16x16x32_bf16 v[34:37], v[90:93], v[42:45], v[46:49]
	v_cmp_lt_i32_e32 vcc, v198, v196
	s_nop 1
	v_cndmask_b32_e32 v0, v195, v198, vcc
	v_lshlrev_b32_e32 v42, 2, v0
	v_max3_f32 v0, v70, s18, v71
	v_max3_f32 v0, v0, v72, v73
	v_max3_f32 v0, v0, v66, v67
	v_max3_f32 v0, v0, v68, v69
	v_max3_f32 v0, v0, v62, v63
	v_max3_f32 v0, v0, v64, v65
	v_max3_f32 v0, v0, v38, v39
	v_max3_f32 v0, v0, v40, v41
	v_mul_f32_e32 v0, 0x3e38aa3b, v0
	v_mov_b32_e32 v44, v0
	s_nop 1
	v_permlane16_swap_b32_e32 v44, v0
	v_cmp_lt_i32_e32 vcc, v197, v196
	v_max_f32_e32 v44, v44, v44
	v_cndmask_b32_e32 v43, v195, v197, vcc
	v_lshlrev_b32_e32 v43, 2, v43
	v_max_f32_e32 v0, v0, v44
	v_mov_b32_e32 v44, v0
	s_nop 1
	v_permlane32_swap_b32_e32 v44, v0
	v_max_f32_e32 v44, v44, v44
	v_max_f32_e32 v0, v0, v44
	v_add_f32_e32 v44, 0x41000000, v144
	v_cmp_gt_f32_e32 vcc, v0, v44
	s_cbranch_vccz .LBB0_421
	v_max_f32_e32 v0, v0, v0
	v_max_f32_e32 v44, v144, v144
	v_max_f32_e32 v44, v44, v0
	v_sub_f32_e32 v0, v144, v44
	v_exp_f32_e32 v0, v0
	v_mov_b32_e32 v144, v44
	v_mul_f32_e32 v140, v140, v0
	v_pk_mul_f32 v[20:21], v[20:21], v[0:1] op_sel_hi:[1,0]
	v_pk_mul_f32 v[18:19], v[18:19], v[0:1] op_sel_hi:[1,0]
	v_pk_mul_f32 v[24:25], v[24:25], v[0:1] op_sel_hi:[1,0]
	v_pk_mul_f32 v[22:23], v[22:23], v[0:1] op_sel_hi:[1,0]
	v_pk_mul_f32 v[12:13], v[12:13], v[0:1] op_sel_hi:[1,0]
	v_pk_mul_f32 v[10:11], v[10:11], v[0:1] op_sel_hi:[1,0]
	v_pk_mul_f32 v[4:5], v[4:5], v[0:1] op_sel_hi:[1,0]
	v_pk_mul_f32 v[2:3], v[2:3], v[0:1] op_sel_hi:[1,0]
.LBB0_421:
	v_max3_f32 v0, v58, s18, v59
	v_max3_f32 v0, v0, v60, v61
	v_max3_f32 v0, v0, v54, v55
	v_max3_f32 v0, v0, v56, v57
	v_max3_f32 v0, v0, v50, v51
	v_max3_f32 v0, v0, v52, v53
	v_max3_f32 v0, v0, v34, v35
	v_max3_f32 v0, v0, v36, v37
	v_mul_f32_e32 v0, 0x3e38aa3b, v0
	v_mov_b32_e32 v44, v0
	s_nop 1
	v_permlane16_swap_b32_e32 v44, v0
	v_readlane_b32 s15, v255, 34
	v_max_f32_e32 v44, v44, v44
	v_max_f32_e32 v0, v0, v44
	v_mov_b32_e32 v44, v0
	s_nop 1
	v_permlane32_swap_b32_e32 v44, v0
	v_max_f32_e32 v44, v44, v44
	v_max_f32_e32 v0, v0, v44
	v_add_f32_e32 v44, 0x41000000, v142
	v_cmp_gt_f32_e32 vcc, v0, v44
	s_cbranch_vccz .LBB0_332
	v_max_f32_e32 v0, v0, v0
	v_max_f32_e32 v44, v142, v142
	v_max_f32_e32 v44, v44, v0
	v_sub_f32_e32 v0, v142, v44
	v_exp_f32_e32 v0, v0
	v_mov_b32_e32 v142, v44
	v_mul_f32_e32 v137, v137, v0
	v_pk_mul_f32 v[32:33], v[32:33], v[0:1] op_sel_hi:[1,0]
	v_pk_mul_f32 v[30:31], v[30:31], v[0:1] op_sel_hi:[1,0]
	v_pk_mul_f32 v[28:29], v[28:29], v[0:1] op_sel_hi:[1,0]
	v_pk_mul_f32 v[26:27], v[26:27], v[0:1] op_sel_hi:[1,0]
	v_pk_mul_f32 v[16:17], v[16:17], v[0:1] op_sel_hi:[1,0]
	v_pk_mul_f32 v[14:15], v[14:15], v[0:1] op_sel_hi:[1,0]
	v_pk_mul_f32 v[8:9], v[8:9], v[0:1] op_sel_hi:[1,0]
	v_pk_mul_f32 v[6:7], v[6:7], v[0:1] op_sel_hi:[1,0]
	s_branch .LBB0_332

.LBB0_554:
	v_mov_b32_e32 v0, v141
	s_nop 1
	v_permlane16_swap_b32_e32 v0, v141
	v_readlane_b32 s4, v254, 38
	v_readlane_b32 s5, v254, 39
	s_add_i32 s6, s6, 1
	s_cmp_eq_u32 s6, 8
	v_add_f32_e32 v0, v141, v0
	v_mov_b32_e32 v2, v0
	s_nop 1
	v_permlane32_swap_b32_e32 v2, v0
	v_add_f32_e32 v0, v0, v2
	v_div_scale_f32 v4, s[2:3], v0, v0, 1.0
	v_rcp_f32_e32 v5, v4
	v_div_scale_f32 v6, vcc, 1.0, v0, 1.0
	v_lshlrev_b64 v[2:3], 11, v[112:113]
	v_fma_f32 v7, -v4, v5, 1.0
	v_fmac_f32_e32 v5, v7, v5
	v_mul_f32_e32 v7, v6, v5
	v_fma_f32 v8, -v4, v7, v6
	v_fmac_f32_e32 v7, v8, v5
	v_fma_f32 v4, -v4, v7, v6
	v_div_fmas_f32 v4, v4, v5, v7
	v_div_fixup_f32 v4, v4, v0, 1.0
	v_pk_mul_f32 v[8:9], v[76:77], v[4:5] op_sel_hi:[1,0]
	v_pk_mul_f32 v[6:7], v[74:75], v[4:5] op_sel_hi:[1,0]
	v_bfe_u32 v0, v9, 16, 1
	v_bfe_u32 v5, v8, 16, 1
	v_add3_u32 v5, v8, v5, s0
	v_add3_u32 v0, v9, v0, s0
	v_mov_b32_e32 v10, v7
	v_perm_b32 v7, v0, v5, s19
	v_lshl_add_u64 v[2:3], s[4:5], 0, v[2:3]
	v_lshlrev_b32_e32 v0, 1, v131
	v_cvt_pk_bf16_f32 v6, v6, v10
	v_lshl_add_u64 v[2:3], v[2:3], 0, v[0:1]
	global_store_dwordx2 v[2:3], v[6:7], off
	v_pk_mul_f32 v[6:7], v[70:71], v[4:5] op_sel_hi:[1,0]
	v_pk_mul_f32 v[8:9], v[72:73], v[4:5] op_sel_hi:[1,0]
	v_bfe_u32 v5, v9, 16, 1
	v_bfe_u32 v10, v8, 16, 1
	v_mov_b32_e32 v11, v7
	v_add3_u32 v7, v8, v10, s0
	v_add3_u32 v5, v9, v5, s0
	v_perm_b32 v7, v5, v7, s19
	v_cvt_pk_bf16_f32 v6, v6, v11
	global_store_dwordx2 v[2:3], v[6:7], off offset:32
	v_pk_mul_f32 v[6:7], v[66:67], v[4:5] op_sel_hi:[1,0]
	v_pk_mul_f32 v[8:9], v[68:69], v[4:5] op_sel_hi:[1,0]
	v_bfe_u32 v10, v8, 16, 1
	v_mov_b32_e32 v11, v7
	v_add3_u32 v7, v8, v10, s0
	v_mov_b32_e32 v8, v140
	s_nop 1
	v_permlane16_swap_b32_e32 v8, v140
	v_bfe_u32 v5, v9, 16, 1
	v_add3_u32 v5, v9, v5, s0
	v_add_f32_e32 v8, v140, v8
	v_mov_b32_e32 v13, v8
	s_nop 1
	v_permlane32_swap_b32_e32 v13, v8
	v_perm_b32 v7, v5, v7, s19
	v_cvt_pk_bf16_f32 v6, v6, v11
	global_store_dwordx2 v[2:3], v[6:7], off offset:64
	v_pk_mul_f32 v[6:7], v[62:63], v[4:5] op_sel_hi:[1,0]
	v_pk_mul_f32 v[4:5], v[64:65], v[4:5] op_sel_hi:[1,0]
	v_add_f32_e32 v8, v8, v13
	v_div_scale_f32 v9, s[2:3], v8, v8, 1.0
	v_rcp_f32_e32 v10, v9
	v_cvt_pk_bf16_f32 v5, v4, v5
	v_cvt_pk_bf16_f32 v4, v6, v7
	global_store_dwordx2 v[2:3], v[4:5], off offset:96
	v_fma_f32 v2, -v9, v10, 1.0
	v_fmac_f32_e32 v10, v2, v10
	v_div_scale_f32 v2, vcc, 1.0, v8, 1.0
	v_mul_f32_e32 v3, v2, v10
	v_fma_f32 v4, -v9, v3, v2
	v_fmac_f32_e32 v3, v4, v10
	v_fma_f32 v2, -v9, v3, v2
	v_div_fmas_f32 v2, v2, v10, v3
	v_div_fixup_f32 v2, v2, v8, 1.0
	v_pk_mul_f32 v[6:7], v[58:59], v[2:3] op_sel_hi:[1,0]
	v_pk_mul_f32 v[8:9], v[60:61], v[2:3] op_sel_hi:[1,0]
	v_lshlrev_b64 v[4:5], 11, v[110:111]
	v_bfe_u32 v3, v9, 16, 1
	v_bfe_u32 v10, v8, 16, 1
	v_mov_b32_e32 v11, v7
	v_add3_u32 v7, v8, v10, s0
	v_add3_u32 v3, v9, v3, s0
	v_lshl_add_u64 v[4:5], s[4:5], 0, v[4:5]
	v_perm_b32 v7, v3, v7, s19
	v_cvt_pk_bf16_f32 v6, v6, v11
	v_lshl_add_u64 v[4:5], v[4:5], 0, v[0:1]
	global_store_dwordx2 v[4:5], v[6:7], off
	v_pk_mul_f32 v[6:7], v[54:55], v[2:3] op_sel_hi:[1,0]
	v_pk_mul_f32 v[8:9], v[56:57], v[2:3] op_sel_hi:[1,0]
	v_bfe_u32 v0, v9, 16, 1
	v_bfe_u32 v3, v8, 16, 1
	v_mov_b32_e32 v10, v7
	v_add3_u32 v3, v8, v3, s0
	v_add3_u32 v0, v9, v0, s0
	v_perm_b32 v7, v0, v3, s19
	v_cvt_pk_bf16_f32 v6, v6, v10
	global_store_dwordx2 v[4:5], v[6:7], off offset:32
	v_pk_mul_f32 v[6:7], v[50:51], v[2:3] op_sel_hi:[1,0]
	v_pk_mul_f32 v[8:9], v[52:53], v[2:3] op_sel_hi:[1,0]
	v_bfe_u32 v0, v9, 16, 1
	v_bfe_u32 v3, v8, 16, 1
	v_mov_b32_e32 v10, v7
	v_add3_u32 v3, v8, v3, s0
	v_add3_u32 v0, v9, v0, s0
	v_perm_b32 v7, v0, v3, s19
	v_cvt_pk_bf16_f32 v6, v6, v10
	global_store_dwordx2 v[4:5], v[6:7], off offset:64
	v_pk_mul_f32 v[6:7], v[46:47], v[2:3] op_sel_hi:[1,0]
	v_pk_mul_f32 v[2:3], v[48:49], v[2:3] op_sel_hi:[1,0]
	v_cvt_pk_bf16_f32 v3, v2, v3
	v_cvt_pk_bf16_f32 v2, v6, v7
	global_store_dwordx2 v[4:5], v[2:3], off offset:96
	s_cbranch_scc1 .LBB0_588
